# stagger 2 sleeps (~7 us)
# speedup vs baseline: 1.0087x; 1.0049x over previous
.LBB0_539:
	s_or_b64 exec, exec, s[0:1]
	v_mov_b32_e32 v0, v154
	v_readlane_b32 s6, v253, 0
	s_waitcnt lgkmcnt(0)
	s_barrier
	v_readlane_b32 s8, v253, 0
	s_bitcmp1_b32 s8, 0
	s_cbranch_scc0 .Lstag_skip
	s_sleep 127
	s_sleep 127
.Lstag_skip:
	s_cmpk_gt_i32 s6, 0xff
	s_cbranch_scc1 .LBB0_546
	v_readlane_b32 s0, v254, 24
	v_readlane_b32 s1, v254, 60
	s_add_u32 s7, s0, s1
	v_readlane_b32 s0, v254, 25
	s_addc_u32 s8, s0, 0
	s_lshl_b32 s9, s6, 3
	s_branch .LBB0_542
